# attention step re-scheduled: key-block-0 softmax in place then first 8 PV MFMAs interleaved with key-block-1 softmax
# baseline (speedup 1.0000x reference)
.LBB0_1384:
	s_add_i32 s0, s34, -2
	s_cmp_lt_i32 s0, 1
	s_cbranch_scc1 .LBB0_1388
	s_waitcnt lgkmcnt(7)
	v_mfma_f32_32x32x16_bf16 v[82:97], v[66:69], v[130:133], 0
	s_waitcnt lgkmcnt(5)
	v_mfma_f32_32x32x16_bf16 v[66:81], v[70:73], v[130:133], 0
	v_mfma_f32_32x32x16_bf16 v[82:97], v[146:149], v[134:137], v[82:97]
	s_waitcnt lgkmcnt(4)
	v_mfma_f32_32x32x16_bf16 v[66:81], v[150:153], v[134:137], v[66:81]
	s_waitcnt lgkmcnt(3)
	v_mfma_f32_32x32x16_bf16 v[82:97], v[154:157], v[138:141], v[82:97]
	s_waitcnt lgkmcnt(1)
	v_mfma_f32_32x32x16_bf16 v[66:81], v[162:165], v[138:141], v[66:81]
	v_mfma_f32_32x32x16_bf16 v[82:97], v[158:161], v[142:145], v[82:97]
	ds_read_b128 v[162:165], v221 offset:17408
	ds_read_b128 v[146:149], v221 offset:17440
	ds_read_b128 v[166:169], v221 offset:22016
	ds_read_b128 v[150:153], v221 offset:22048
	ds_read_b128 v[170:173], v221 offset:26624
	ds_read_b128 v[154:157], v221 offset:26656
	ds_read_b128 v[174:177], v221 offset:31232
	ds_read_b128 v[158:161], v221 offset:31264
	s_waitcnt lgkmcnt(8)
	v_mfma_f32_32x32x16_bf16 v[66:81], v[228:231], v[142:145], v[66:81]
	v_add_u32_e32 v184, s12, v223
	v_add_u32_e32 v184, 0xc0, v184
	v_cvt_f32_i32_e32 v185, v184
	v_mul_f32_e64 v245, -v201, v185
	v_sub_f32_e32 v246, v226, v245
	ds_read_b128 v[228:231], v221 offset:26688
	ds_read_b128 v[232:235], v221 offset:26720
	ds_read_b128 v[236:239], v221 offset:31296
	ds_read_b128 v[240:243], v221 offset:31328
	v_fmamk_f32 v83, v201, 0x3f800000, v83
	v_fmamk_f32 v84, v201, 0x40000000, v84
	v_fmamk_f32 v85, v201, 0x40400000, v85
	v_sub_f32_e32 v82, v82, v246
	v_sub_f32_e32 v83, v83, v246
	v_sub_f32_e32 v84, v84, v246
	v_sub_f32_e32 v85, v85, v246
	v_exp_f32_e32 v82, v82
	v_exp_f32_e32 v83, v83
	v_exp_f32_e32 v84, v84
	v_exp_f32_e32 v85, v85
	v_fmamk_f32 v86, v201, 0x41000000, v86
	v_fmamk_f32 v87, v201, 0x41100000, v87
	v_fmamk_f32 v88, v201, 0x41200000, v88
	v_fmamk_f32 v89, v201, 0x41300000, v89
	v_sub_f32_e32 v86, v86, v246
	v_sub_f32_e32 v87, v87, v246
	v_sub_f32_e32 v88, v88, v246
	v_sub_f32_e32 v89, v89, v246
	v_exp_f32_e32 v86, v86
	v_add_f32_e32 v184, v82, v83
	v_exp_f32_e32 v87, v87
	v_add_f32_e32 v185, v84, v85
	v_exp_f32_e32 v88, v88
	v_exp_f32_e32 v89, v89
	v_fmamk_f32 v90, v201, 0x41800000, v90
	v_fmamk_f32 v91, v201, 0x41880000, v91
	v_fmamk_f32 v92, v201, 0x41900000, v92
	v_fmamk_f32 v93, v201, 0x41980000, v93
	v_sub_f32_e32 v90, v90, v246
	v_sub_f32_e32 v91, v91, v246
	v_sub_f32_e32 v92, v92, v246
	v_sub_f32_e32 v93, v93, v246
	v_exp_f32_e32 v90, v90
	v_add_f32_e32 v184, v184, v86
	v_exp_f32_e32 v91, v91
	v_add_f32_e32 v185, v185, v87
	v_exp_f32_e32 v92, v92
	v_add_f32_e32 v184, v184, v88
	v_exp_f32_e32 v93, v93
	v_add_f32_e32 v185, v185, v89
	v_fmamk_f32 v94, v201, 0x41c00000, v94
	v_fmamk_f32 v95, v201, 0x41c80000, v95
	v_fmamk_f32 v96, v201, 0x41d00000, v96
	v_fmamk_f32 v97, v201, 0x41d80000, v97
	v_sub_f32_e32 v94, v94, v246
	v_sub_f32_e32 v95, v95, v246
	v_sub_f32_e32 v96, v96, v246
	v_sub_f32_e32 v97, v97, v246
	v_exp_f32_e32 v94, v94
	v_add_f32_e32 v184, v184, v90
	v_exp_f32_e32 v95, v95
	v_add_f32_e32 v185, v185, v91
	v_exp_f32_e32 v96, v96
	v_add_f32_e32 v184, v184, v92
	v_exp_f32_e32 v97, v97
	v_add_f32_e32 v185, v185, v93
	v_add_f32_e32 v184, v184, v94
	v_add_f32_e32 v185, v185, v95
	v_add_f32_e32 v184, v184, v96
	v_add_f32_e32 v185, v185, v97
	v_add_f32_e32 v184, v184, v185
	v_add_f32_e32 v224, v224, v184
	v_cvt_pk_bf16_f32 v248, v82, v83
	v_cvt_pk_bf16_f32 v249, v84, v85
	v_cvt_pk_bf16_f32 v250, v86, v87
	v_cvt_pk_bf16_f32 v251, v88, v89
	v_cvt_pk_bf16_f32 v252, v90, v91
	v_cvt_pk_bf16_f32 v253, v92, v93
	v_cvt_pk_bf16_f32 v254, v94, v95
	v_cvt_pk_bf16_f32 v255, v96, v97
	ds_read_b128 v[82:85], v221 offset:17472
	ds_read_b128 v[86:89], v221 offset:17504
	ds_read_b128 v[90:93], v221 offset:22080
	ds_read_b128 v[94:97], v221 offset:22112
	s_waitcnt lgkmcnt(8)
	v_mfma_f32_32x32x16_bf16 v[50:65], v[162:165], v[248:251], v[50:65]
	v_fmamk_f32 v66, v201, 0x42000000, v66
	v_fmamk_f32 v67, v201, 0x42040000, v67
	v_fmamk_f32 v68, v201, 0x42080000, v68
	v_fmamk_f32 v69, v201, 0x420c0000, v69
	v_sub_f32_e32 v66, v66, v246
	v_sub_f32_e32 v67, v67, v246
	v_sub_f32_e32 v68, v68, v246
	v_sub_f32_e32 v69, v69, v246
	v_exp_f32_e32 v66, v66
	v_mfma_f32_32x32x16_bf16 v[34:49], v[166:169], v[248:251], v[34:49]
	v_exp_f32_e32 v67, v67
	v_exp_f32_e32 v68, v68
	v_exp_f32_e32 v69, v69
	v_fmamk_f32 v70, v201, 0x42200000, v70
	v_fmamk_f32 v71, v201, 0x42240000, v71
	v_fmamk_f32 v72, v201, 0x42280000, v72
	v_fmamk_f32 v73, v201, 0x422c0000, v73
	v_sub_f32_e32 v70, v70, v246
	v_sub_f32_e32 v71, v71, v246
	v_mfma_f32_32x32x16_bf16 v[18:33], v[170:173], v[248:251], v[18:33]
	v_sub_f32_e32 v72, v72, v246
	v_sub_f32_e32 v73, v73, v246
	v_exp_f32_e32 v70, v70
	v_add_f32_e32 v188, v66, v67
	v_exp_f32_e32 v71, v71
	v_add_f32_e32 v227, v68, v69
	v_exp_f32_e32 v72, v72
	v_exp_f32_e32 v73, v73
	v_fmamk_f32 v74, v201, 0x42400000, v74
	v_mfma_f32_32x32x16_bf16 v[2:17], v[174:177], v[248:251], v[2:17]
	v_fmamk_f32 v75, v201, 0x42440000, v75
	v_fmamk_f32 v76, v201, 0x42480000, v76
	v_fmamk_f32 v77, v201, 0x424c0000, v77
	v_sub_f32_e32 v74, v74, v246
	v_sub_f32_e32 v75, v75, v246
	v_sub_f32_e32 v76, v76, v246
	v_sub_f32_e32 v77, v77, v246
	v_exp_f32_e32 v74, v74
	v_add_f32_e32 v188, v188, v70
	v_mfma_f32_32x32x16_bf16 v[50:65], v[146:149], v[252:255], v[50:65]
	v_exp_f32_e32 v75, v75
	v_add_f32_e32 v227, v227, v71
	v_exp_f32_e32 v76, v76
	v_add_f32_e32 v188, v188, v72
	v_exp_f32_e32 v77, v77
	v_add_f32_e32 v227, v227, v73
	v_fmamk_f32 v78, v201, 0x42600000, v78
	v_fmamk_f32 v79, v201, 0x42640000, v79
	v_fmamk_f32 v80, v201, 0x42680000, v80
	v_mfma_f32_32x32x16_bf16 v[34:49], v[150:153], v[252:255], v[34:49]
	v_fmamk_f32 v81, v201, 0x426c0000, v81
	v_sub_f32_e32 v78, v78, v246
	v_sub_f32_e32 v79, v79, v246
	v_sub_f32_e32 v80, v80, v246
	v_sub_f32_e32 v81, v81, v246
	v_exp_f32_e32 v78, v78
	v_add_f32_e32 v188, v188, v74
	v_exp_f32_e32 v79, v79
	v_add_f32_e32 v227, v227, v75
	v_mfma_f32_32x32x16_bf16 v[18:33], v[154:157], v[252:255], v[18:33]
	v_exp_f32_e32 v80, v80
	v_add_f32_e32 v188, v188, v76
	v_exp_f32_e32 v81, v81
	v_add_f32_e32 v227, v227, v77
	v_add_f32_e32 v188, v188, v78
	v_add_f32_e32 v227, v227, v79
	v_add_f32_e32 v188, v188, v80
	v_add_f32_e32 v227, v227, v81
	v_add_f32_e32 v188, v188, v227
	v_mfma_f32_32x32x16_bf16 v[2:17], v[158:161], v[252:255], v[2:17]
	v_add_f32_e32 v224, v224, v188
	v_cvt_pk_bf16_f32 v66, v66, v67
	v_cvt_pk_bf16_f32 v67, v68, v69
	v_cvt_pk_bf16_f32 v68, v70, v71
	v_cvt_pk_bf16_f32 v69, v72, v73
	v_cvt_pk_bf16_f32 v70, v74, v75
	v_cvt_pk_bf16_f32 v71, v76, v77
	v_cvt_pk_bf16_f32 v72, v78, v79
	v_cvt_pk_bf16_f32 v73, v80, v81
	s_waitcnt lgkmcnt(0)
	s_nop 1
	v_mfma_f32_32x32x16_bf16 v[50:65], v[82:85], v[66:69], v[50:65]
	v_mfma_f32_32x32x16_bf16 v[34:49], v[90:93], v[66:69], v[34:49]
	v_mfma_f32_32x32x16_bf16 v[18:33], v[228:231], v[66:69], v[18:33]
	v_mfma_f32_32x32x16_bf16 v[2:17], v[236:239], v[66:69], v[2:17]
	v_mfma_f32_32x32x16_bf16 v[50:65], v[86:89], v[70:73], v[50:65]
	v_mfma_f32_32x32x16_bf16 v[34:49], v[94:97], v[70:73], v[34:49]
	v_mfma_f32_32x32x16_bf16 v[18:33], v[232:235], v[70:73], v[18:33]
	v_mfma_f32_32x32x16_bf16 v[2:17], v[240:243], v[70:73], v[2:17]

.LBB0_1398:
	s_waitcnt lgkmcnt(7)
	v_mfma_f32_32x32x16_bf16 v[82:97], v[66:69], v[130:133], 0
	s_waitcnt lgkmcnt(5)
	v_mfma_f32_32x32x16_bf16 v[66:81], v[70:73], v[130:133], 0
	v_mfma_f32_32x32x16_bf16 v[82:97], v[146:149], v[134:137], v[82:97]
	s_waitcnt lgkmcnt(4)
	v_mfma_f32_32x32x16_bf16 v[66:81], v[150:153], v[134:137], v[66:81]
	s_waitcnt lgkmcnt(3)
	v_mfma_f32_32x32x16_bf16 v[82:97], v[154:157], v[138:141], v[82:97]
	s_waitcnt lgkmcnt(1)
	v_mfma_f32_32x32x16_bf16 v[66:81], v[162:165], v[138:141], v[66:81]
	v_mfma_f32_32x32x16_bf16 v[82:97], v[158:161], v[142:145], v[82:97]
	ds_read_b128 v[166:169], v221 offset:53248
	ds_read_b128 v[150:153], v221 offset:53280
	ds_read_b128 v[162:165], v225 offset:13824
	ds_read_b128 v[146:149], v225 offset:13856
	ds_read_b128 v[170:173], v221 offset:57856
	ds_read_b128 v[154:157], v221 offset:57888
	ds_read_b128 v[174:177], v221 offset:62464
	ds_read_b128 v[158:161], v221 offset:62496
	s_waitcnt lgkmcnt(8)
	v_mfma_f32_32x32x16_bf16 v[66:81], v[228:231], v[142:145], v[66:81]
	v_add_u32_e32 v184, s12, v223
	v_add_u32_e32 v184, 0x100, v184
	v_cvt_f32_i32_e32 v185, v184
	v_mul_f32_e64 v245, -v201, v185
	v_sub_f32_e32 v246, v226, v245
	ds_read_b128 v[228:231], v221 offset:62528
	ds_read_b128 v[232:235], v221 offset:62560
	ds_read_b128 v[236:239], v225 offset:13888
	ds_read_b128 v[240:243], v225 offset:13920
	v_fmamk_f32 v83, v201, 0x3f800000, v83
	v_fmamk_f32 v84, v201, 0x40000000, v84
	v_fmamk_f32 v85, v201, 0x40400000, v85
	v_sub_f32_e32 v82, v82, v246
	v_sub_f32_e32 v83, v83, v246
	v_sub_f32_e32 v84, v84, v246
	v_sub_f32_e32 v85, v85, v246
	v_exp_f32_e32 v82, v82
	v_exp_f32_e32 v83, v83
	v_exp_f32_e32 v84, v84
	v_exp_f32_e32 v85, v85
	v_fmamk_f32 v86, v201, 0x41000000, v86
	v_fmamk_f32 v87, v201, 0x41100000, v87
	v_fmamk_f32 v88, v201, 0x41200000, v88
	v_fmamk_f32 v89, v201, 0x41300000, v89
	v_sub_f32_e32 v86, v86, v246
	v_sub_f32_e32 v87, v87, v246
	v_sub_f32_e32 v88, v88, v246
	v_sub_f32_e32 v89, v89, v246
	v_exp_f32_e32 v86, v86
	v_add_f32_e32 v184, v82, v83
	v_exp_f32_e32 v87, v87
	v_add_f32_e32 v185, v84, v85
	v_exp_f32_e32 v88, v88
	v_exp_f32_e32 v89, v89
	v_fmamk_f32 v90, v201, 0x41800000, v90
	v_fmamk_f32 v91, v201, 0x41880000, v91
	v_fmamk_f32 v92, v201, 0x41900000, v92
	v_fmamk_f32 v93, v201, 0x41980000, v93
	v_sub_f32_e32 v90, v90, v246
	v_sub_f32_e32 v91, v91, v246
	v_sub_f32_e32 v92, v92, v246
	v_sub_f32_e32 v93, v93, v246
	v_exp_f32_e32 v90, v90
	v_add_f32_e32 v184, v184, v86
	v_exp_f32_e32 v91, v91
	v_add_f32_e32 v185, v185, v87
	v_exp_f32_e32 v92, v92
	v_add_f32_e32 v184, v184, v88
	v_exp_f32_e32 v93, v93
	v_add_f32_e32 v185, v185, v89
	v_fmamk_f32 v94, v201, 0x41c00000, v94
	v_fmamk_f32 v95, v201, 0x41c80000, v95
	v_fmamk_f32 v96, v201, 0x41d00000, v96
	v_fmamk_f32 v97, v201, 0x41d80000, v97
	v_sub_f32_e32 v94, v94, v246
	v_sub_f32_e32 v95, v95, v246
	v_sub_f32_e32 v96, v96, v246
	v_sub_f32_e32 v97, v97, v246
	v_exp_f32_e32 v94, v94
	v_add_f32_e32 v184, v184, v90
	v_exp_f32_e32 v95, v95
	v_add_f32_e32 v185, v185, v91
	v_exp_f32_e32 v96, v96
	v_add_f32_e32 v184, v184, v92
	v_exp_f32_e32 v97, v97
	v_add_f32_e32 v185, v185, v93
	v_add_f32_e32 v184, v184, v94
	v_add_f32_e32 v185, v185, v95
	v_add_f32_e32 v184, v184, v96
	v_add_f32_e32 v185, v185, v97
	v_add_f32_e32 v184, v184, v185
	v_add_f32_e32 v224, v224, v184
	v_cvt_pk_bf16_f32 v248, v82, v83
	v_cvt_pk_bf16_f32 v249, v84, v85
	v_cvt_pk_bf16_f32 v250, v86, v87
	v_cvt_pk_bf16_f32 v251, v88, v89
	v_cvt_pk_bf16_f32 v252, v90, v91
	v_cvt_pk_bf16_f32 v253, v92, v93
	v_cvt_pk_bf16_f32 v254, v94, v95
	v_cvt_pk_bf16_f32 v255, v96, v97
	ds_read_b128 v[82:85], v221 offset:53312
	ds_read_b128 v[86:89], v221 offset:53344
	ds_read_b128 v[90:93], v221 offset:57920
	ds_read_b128 v[94:97], v221 offset:57952
	s_waitcnt lgkmcnt(8)
	v_mfma_f32_32x32x16_bf16 v[50:65], v[166:169], v[248:251], v[50:65]
	v_fmamk_f32 v66, v201, 0x42000000, v66
	v_fmamk_f32 v67, v201, 0x42040000, v67
	v_fmamk_f32 v68, v201, 0x42080000, v68
	v_fmamk_f32 v69, v201, 0x420c0000, v69
	v_sub_f32_e32 v66, v66, v246
	v_sub_f32_e32 v67, v67, v246
	v_sub_f32_e32 v68, v68, v246
	v_sub_f32_e32 v69, v69, v246
	v_exp_f32_e32 v66, v66
	v_mfma_f32_32x32x16_bf16 v[34:49], v[170:173], v[248:251], v[34:49]
	v_exp_f32_e32 v67, v67
	v_exp_f32_e32 v68, v68
	v_exp_f32_e32 v69, v69
	v_fmamk_f32 v70, v201, 0x42200000, v70
	v_fmamk_f32 v71, v201, 0x42240000, v71
	v_fmamk_f32 v72, v201, 0x42280000, v72
	v_fmamk_f32 v73, v201, 0x422c0000, v73
	v_sub_f32_e32 v70, v70, v246
	v_sub_f32_e32 v71, v71, v246
	v_mfma_f32_32x32x16_bf16 v[18:33], v[174:177], v[248:251], v[18:33]
	v_sub_f32_e32 v72, v72, v246
	v_sub_f32_e32 v73, v73, v246
	v_exp_f32_e32 v70, v70
	v_add_f32_e32 v188, v66, v67
	v_exp_f32_e32 v71, v71
	v_add_f32_e32 v227, v68, v69
	v_exp_f32_e32 v72, v72
	v_exp_f32_e32 v73, v73
	v_fmamk_f32 v74, v201, 0x42400000, v74
	v_mfma_f32_32x32x16_bf16 v[2:17], v[162:165], v[248:251], v[2:17]
	v_fmamk_f32 v75, v201, 0x42440000, v75
	v_fmamk_f32 v76, v201, 0x42480000, v76
	v_fmamk_f32 v77, v201, 0x424c0000, v77
	v_sub_f32_e32 v74, v74, v246
	v_sub_f32_e32 v75, v75, v246
	v_sub_f32_e32 v76, v76, v246
	v_sub_f32_e32 v77, v77, v246
	v_exp_f32_e32 v74, v74
	v_add_f32_e32 v188, v188, v70
	v_mfma_f32_32x32x16_bf16 v[50:65], v[150:153], v[252:255], v[50:65]
	v_exp_f32_e32 v75, v75
	v_add_f32_e32 v227, v227, v71
	v_exp_f32_e32 v76, v76
	v_add_f32_e32 v188, v188, v72
	v_exp_f32_e32 v77, v77
	v_add_f32_e32 v227, v227, v73
	v_fmamk_f32 v78, v201, 0x42600000, v78
	v_fmamk_f32 v79, v201, 0x42640000, v79
	v_fmamk_f32 v80, v201, 0x42680000, v80
	v_mfma_f32_32x32x16_bf16 v[34:49], v[154:157], v[252:255], v[34:49]
	v_fmamk_f32 v81, v201, 0x426c0000, v81
	v_sub_f32_e32 v78, v78, v246
	v_sub_f32_e32 v79, v79, v246
	v_sub_f32_e32 v80, v80, v246
	v_sub_f32_e32 v81, v81, v246
	v_exp_f32_e32 v78, v78
	v_add_f32_e32 v188, v188, v74
	v_exp_f32_e32 v79, v79
	v_add_f32_e32 v227, v227, v75
	v_mfma_f32_32x32x16_bf16 v[18:33], v[158:161], v[252:255], v[18:33]
	v_exp_f32_e32 v80, v80
	v_add_f32_e32 v188, v188, v76
	v_exp_f32_e32 v81, v81
	v_add_f32_e32 v227, v227, v77
	v_add_f32_e32 v188, v188, v78
	v_add_f32_e32 v227, v227, v79
	v_add_f32_e32 v188, v188, v80
	v_add_f32_e32 v227, v227, v81
	v_add_f32_e32 v188, v188, v227
	v_mfma_f32_32x32x16_bf16 v[2:17], v[146:149], v[252:255], v[2:17]
	v_add_f32_e32 v224, v224, v188
	v_cvt_pk_bf16_f32 v66, v66, v67
	v_cvt_pk_bf16_f32 v67, v68, v69
	v_cvt_pk_bf16_f32 v68, v70, v71
	v_cvt_pk_bf16_f32 v69, v72, v73
	v_cvt_pk_bf16_f32 v70, v74, v75
	v_cvt_pk_bf16_f32 v71, v76, v77
	v_cvt_pk_bf16_f32 v72, v78, v79
	v_cvt_pk_bf16_f32 v73, v80, v81
	s_waitcnt lgkmcnt(0)
	s_nop 1
	v_mfma_f32_32x32x16_bf16 v[50:65], v[82:85], v[66:69], v[50:65]
	v_mfma_f32_32x32x16_bf16 v[34:49], v[90:93], v[66:69], v[34:49]
	v_mfma_f32_32x32x16_bf16 v[18:33], v[228:231], v[66:69], v[18:33]
	v_mfma_f32_32x32x16_bf16 v[2:17], v[236:239], v[66:69], v[2:17]
	v_mfma_f32_32x32x16_bf16 v[50:65], v[86:89], v[70:73], v[50:65]
	v_mfma_f32_32x32x16_bf16 v[34:49], v[94:97], v[70:73], v[34:49]
	v_mfma_f32_32x32x16_bf16 v[18:33], v[232:235], v[70:73], v[18:33]
	v_mfma_f32_32x32x16_bf16 v[2:17], v[240:243], v[70:73], v[2:17]
	s_cmp_ge_i32 s46, s26
	s_cbranch_scc1 .LBB0_1379
